# PLE-up small tiles assigned only to the light work-groups of the in-proj GEMM (stride G-r1)
# speedup vs baseline: 1.0060x; 1.0050x over previous
.LBB0_804:
	v_readlane_b32 s2, v254, 22
	s_mul_i32 s0, s49, s2
	s_mul_hi_u32 s1, s48, s2
	s_add_i32 s0, s1, s0
	s_mul_i32 s0, s0, s77
	s_sub_i32 s0, s48, s0
	s_sub_i32 s1, s0, s77
	s_cmp_ge_u32 s0, s77
	s_cselect_b32 s0, s1, s0
	s_sub_i32 s1, s0, s77
	s_cmp_ge_u32 s0, s77
	s_cselect_b32 s0, s1, s0
	s_sub_i32 s100, s46, s0
	s_ashr_i32 s101, s100, 31
	v_readlane_b32 s1, v254, 59
	s_add_i32 s1, s1, s46
	s_sub_i32 s0, s1, s0
	s_ashr_i32 s1, s0, 31
	s_abs_i32 s0, s0
	s_mul_hi_u32 s2, s0, s2
	s_mul_i32 s2, s2, s77
	s_sub_i32 s0, s0, s2
	s_sub_i32 s2, s0, s77
	s_cmp_ge_u32 s0, s77
	s_cselect_b32 s0, s2, s0
	s_sub_i32 s2, s0, s77
	s_cmp_ge_u32 s0, s77
	s_cselect_b32 s0, s2, s0
	s_xor_b32 s0, s0, s1
	s_sub_i32 s4, s0, s1
	s_waitcnt lgkmcnt(0)
	v_mov_b32_e32 v2, v142
	v_readlane_b32 s0, v255, 2
	s_cmp_ge_i32 s4, s100
	s_cselect_b32 s4, 0x7fff, s4
	s_cmpk_gt_i32 s4, 0x10f
	v_readfirstlane_b32 s5, v2
	s_mov_b32 s22, s0
	s_cbranch_scc1 .LBB0_816
	v_lshlrev_b32_e32 v0, 4, v2
	v_add_u32_e32 v3, 0x2000, v0
	v_ashrrev_i32_e32 v4, 31, v3
	v_lshrrev_b32_e32 v4, 22, v4
	v_add_u32_e32 v4, v3, v4
	v_ashrrev_i32_e32 v4, 10, v4
	v_mul_i32_i24_e32 v5, 0x400, v4
	v_sub_u32_e32 v3, v3, v5
	v_lshrrev_b32_e32 v5, 4, v3
	v_readlane_b32 s6, v255, 6
	v_bitop3_b32 v3, v5, v3, 32 bitop3:0x6c
	s_mul_i32 s1, s6, 0x880000
	v_readlane_b32 s2, v254, 62
	v_ashrrev_i32_e32 v5, 31, v3
	v_readlane_b32 s7, v255, 7
	s_mul_hi_i32 s0, s6, 0x880000
	v_readlane_b32 s3, v254, 63
	s_add_u32 s33, s2, s1
	v_lshrrev_b32_e32 v5, 26, v5
	s_addc_u32 s34, s3, s0
	s_lshl_b64 s[0:1], s[6:7], 19
	v_add_u32_e32 v5, v3, v5
	v_lshlrev_b32_e32 v7, 3, v4
	s_add_u32 s0, s50, s0
	v_ashrrev_i32_e32 v6, 6, v5
	v_and_b32_e32 v7, -16, v7
	v_and_b32_e32 v5, 0xc0, v5
	s_addc_u32 s1, s51, s1
	v_add_u32_e32 v7, v6, v7
	v_sub_u32_e32 v3, v3, v5
	s_add_u32 s35, s0, 0x7700000
	v_and_b32_e32 v6, 3, v6
	s_mov_b32 s0, 0x7fffe0
	v_lshrrev_b32_e32 v8, 2, v7
	v_lshlrev_b32_e32 v9, 1, v7
	v_lshlrev_b32_e32 v4, 5, v4
	v_ashrrev_i16_sdwa v3, v252, sext(v3) dst_sel:DWORD dst_unused:UNUSED_PAD src0_sel:DWORD src1_sel:BYTE_0
	v_and_or_b32 v6, v7, s0, v6
	v_and_b32_e32 v8, 4, v8
	v_and_b32_e32 v9, 24, v9
	v_and_b32_e32 v4, 32, v4
	v_bfe_i32 v3, v3, 0, 16
	v_or3_b32 v6, v6, v8, v9
	v_add_lshl_u32 v3, v4, v3, 1
	v_lshl_add_u32 v130, v6, 9, v3
	v_lshl_add_u32 v132, v7, 9, v3
	v_bfe_i32 v3, v2, 27, 1
	v_lshrrev_b32_e32 v3, 22, v3
	v_add_u32_e32 v3, v0, v3
	v_and_b32_e32 v3, 0xfffffc00, v3
	v_sub_u32_e32 v0, v0, v3
	v_ashrrev_i32_e32 v4, 31, v2
	v_lshrrev_b32_e32 v3, 4, v0
	v_lshrrev_b32_e32 v4, 26, v4
	v_bitop3_b32 v3, v3, v0, 32 bitop3:0x6c
	v_ashrrev_i32_e32 v0, 31, v0
	v_add_u32_e32 v4, v2, v4
	v_lshrrev_b32_e32 v0, 26, v0
	v_ashrrev_i32_e32 v4, 6, v4
	v_add_u32_e32 v0, v3, v0
	v_lshlrev_b32_e32 v5, 3, v4
	v_ashrrev_i32_e32 v0, 6, v0
	v_and_b32_e32 v5, -16, v5
	s_addc_u32 s36, s1, 0
	v_add_u32_e32 v5, v0, v5
	v_and_b32_e32 v6, 3, v0
	s_ashr_i32 s37, s4, 31
	v_and_or_b32 v6, v5, s0, v6
	s_lshr_b32 s0, s37, 29
	s_add_i32 s0, s4, s0
	s_ashr_i32 s2, s5, 6
	s_ashr_i32 s6, s0, 3
	s_and_b32 s0, s0, -8
	s_ashr_i32 s3, s5, 8
	s_lshl_b32 s1, s2, 10
	s_sub_i32 s0, s4, s0
	s_cmp_lt_i32 s0, 0
	s_cselect_b32 s7, 35, 34
	s_mul_i32 s0, s0, s7
	s_add_i32 s0, s0, s6
	s_ashr_i32 s6, s0, 31
	s_lshr_b32 s6, s6, 27
	v_mul_i32_i24_e32 v0, 64, v0
	s_add_i32 s6, s0, s6
	v_sub_u32_e32 v0, v3, v0
	s_ashr_i32 s7, s6, 5
	v_lshrrev_b32_e32 v7, 2, v5
	v_lshlrev_b32_e32 v8, 1, v5
	v_lshlrev_b32_e32 v4, 5, v4
	v_ashrrev_i16_sdwa v0, v252, sext(v0) dst_sel:DWORD dst_unused:UNUSED_PAD src0_sel:DWORD src1_sel:BYTE_0
	s_lshl_b32 s8, s7, 3
	v_and_b32_e32 v7, 4, v7
	v_and_b32_e32 v8, 24, v8
	v_and_b32_e32 v4, 32, v4
	v_bfe_i32 v0, v0, 0, 16
	s_sub_i32 s7, 0x44, s8
	v_or3_b32 v6, v6, v7, v8
	v_add_lshl_u32 v3, v4, v0, 1
	s_min_u32 s9, s7, 8
	s_andn2_b32 s6, s6, 31
	v_lshl_add_u32 v0, v6, 9, v3
	s_sub_i32 s10, s0, s6
	v_cvt_f32_ubyte0_e32 v6, s9
	v_cvt_f32_i32_e32 v4, s10
	v_rcp_iflag_f32_e32 v7, v6
	v_lshl_add_u32 v134, v5, 9, v3
	s_ashr_i32 s0, s10, 30
	s_or_b32 s0, s0, 1
	v_mul_f32_e32 v3, v4, v7
	v_trunc_f32_e32 v3, v3
	v_fma_f32 v4, -v3, v6, v4
	v_cvt_i32_f32_e32 v3, v3
	v_cmp_ge_f32_e64 s[6:7], |v4|, v6
	s_and_b64 s[6:7], s[6:7], exec
	s_cselect_b32 s0, s0, 0
	v_readfirstlane_b32 s6, v3
	s_add_i32 s0, s6, s0
	s_mul_i32 s6, s0, s9
	s_sub_i32 s6, s10, s6
	s_sext_i32_i8 s6, s6
	s_add_i32 s12, s8, s6
	s_ashr_i32 s13, s12, 31
	s_bfe_i64 s[8:9], s[0:1], 0x80000
	s_lshl_b64 s[6:7], s[12:13], 17
	s_lshl_b64 s[8:9], s[8:9], 17
	s_add_u32 s14, s35, s8
	s_addc_u32 s15, s36, s9
	s_add_i32 s13, s89, 0x10000
	s_add_i32 s38, s13, s1
	s_add_i32 s39, s38, 0x2000
	s_add_u32 s16, s33, s6
	s_addc_u32 s17, s34, s7
	s_add_i32 s40, s89, s1
	s_mov_b32 m0, s38
	s_add_i32 s41, s40, 0x2000
	global_load_lds_dwordx4 v0, s[14:15]
	s_mov_b32 m0, s39
	s_add_u32 s6, s14, 0x10000
	global_load_lds_dwordx4 v130, s[14:15]
	s_mov_b32 m0, s40
	s_addc_u32 s7, s15, 0
	s_add_i32 s42, s89, 0x14000
	global_load_lds_dwordx4 v134, s[16:17]
	s_mov_b32 m0, s41
	s_add_i32 s43, s42, s1
	global_load_lds_dwordx4 v132, s[16:17]
	s_mov_b32 m0, s43
	s_add_i32 s44, s43, 0x2000
	global_load_lds_dwordx4 v0, s[6:7]
	s_mov_b32 m0, s44
	s_nop 0
	global_load_lds_dwordx4 v130, s[6:7]
	s_add_u32 s6, s16, 0x10000
	s_addc_u32 s7, s17, 0
	s_add_i32 s45, s40, 0x4000
	s_mov_b32 m0, s45
	s_add_i32 s48, s40, 0x6000
	global_load_lds_dwordx4 v134, s[6:7]
	s_mov_b32 m0, s48
	s_cmp_lg_u32 s3, 1
	global_load_lds_dwordx4 v132, s[6:7]
	s_cbranch_scc1 .LBB0_807
	s_barrier

.LBB0_808:
	s_add_i32 s63, s63, 1
	s_mul_i32 s1, s63, s101
	s_mul_hi_u32 s3, s63, s100
	s_add_i32 s3, s3, s1
	s_mul_i32 s1, s63, s100
	s_add_u32 s8, s1, s4
	s_addc_u32 s9, s3, s37
	v_cmp_gt_i64_e64 s[6:7], s[8:9], v[148:149]
	s_and_b64 vcc, exec, s[6:7]
	s_cbranch_vccnz .LBB0_810
	s_ashr_i32 s0, s8, 31
	s_lshr_b32 s0, s0, 29
	s_add_i32 s0, s8, s0
	s_ashr_i32 s1, s0, 3
	s_and_b32 s0, s0, -8
	s_sub_i32 s0, s8, s0
	s_cmp_lt_i32 s0, 0
	s_cselect_b32 s2, 35, 34
	s_mul_i32 s0, s0, s2
	s_add_i32 s0, s0, s1
	s_ashr_i32 s1, s0, 31
	s_lshr_b32 s1, s1, 27
	s_add_i32 s1, s0, s1
	s_ashr_i32 s2, s1, 5
	s_lshl_b32 s2, s2, 3
	s_sub_i32 s3, 0x44, s2
	s_min_i32 s3, s3, 8
	s_abs_i32 s10, s3
	v_cvt_f32_u32_e32 v2, s10
	s_sub_i32 s18, 0, s10
	s_andn2_b32 s1, s1, 31
	s_sub_i32 s1, s0, s1
	v_rcp_iflag_f32_e32 v2, v2
	s_abs_i32 s0, s1
	s_xor_b32 s11, s1, s3
	s_ashr_i32 s11, s11, 31
	v_mul_f32_e32 v2, 0x4f7ffffe, v2
	v_cvt_u32_f32_e32 v2, v2
	s_nop 0
	v_readfirstlane_b32 s19, v2
	s_mul_i32 s18, s18, s19
	s_mul_hi_u32 s18, s19, s18
	s_add_i32 s19, s19, s18
	s_mul_hi_u32 s18, s0, s19
	s_mul_i32 s19, s18, s10
	s_sub_i32 s0, s0, s19
	s_add_i32 s20, s18, 1
	s_sub_i32 s19, s0, s10
	s_cmp_ge_u32 s0, s10
	s_cselect_b32 s18, s20, s18
	s_cselect_b32 s0, s19, s0
	s_add_i32 s19, s18, 1
	s_cmp_ge_u32 s0, s10
	s_cselect_b32 s0, s19, s18
	s_xor_b32 s0, s0, s11
	s_sub_i32 s0, s0, s11
	s_mul_i32 s3, s0, s3
	s_sub_i32 s1, s1, s3
	s_add_i32 s2, s2, s1

	.amdhsa_kernel _Z4mega6Params
		.amdhsa_group_segment_fixed_size 0
		.amdhsa_private_segment_fixed_size 0
		.amdhsa_kernarg_size 576
		.amdhsa_user_sgpr_count 2
		.amdhsa_user_sgpr_dispatch_ptr 0
		.amdhsa_user_sgpr_queue_ptr 0
		.amdhsa_user_sgpr_kernarg_segment_ptr 1
		.amdhsa_user_sgpr_dispatch_id 0
		.amdhsa_user_sgpr_kernarg_preload_length 0
		.amdhsa_user_sgpr_kernarg_preload_offset 0
		.amdhsa_user_sgpr_private_segment_size 0
		.amdhsa_uses_dynamic_stack 0
		.amdhsa_enable_private_segment 0
		.amdhsa_system_sgpr_workgroup_id_x 1
		.amdhsa_system_sgpr_workgroup_id_y 0
		.amdhsa_system_sgpr_workgroup_id_z 0
		.amdhsa_system_sgpr_workgroup_info 0
		.amdhsa_system_vgpr_workitem_id 2
		.amdhsa_next_free_vgpr 256
		.amdhsa_next_free_sgpr 102
		.amdhsa_accum_offset 256
		.amdhsa_reserve_vcc 1
		.amdhsa_float_round_mode_32 0
		.amdhsa_float_round_mode_16_64 0
		.amdhsa_float_denorm_mode_32 3
		.amdhsa_float_denorm_mode_16_64 3
		.amdhsa_dx10_clamp 1
		.amdhsa_ieee_mode 1
		.amdhsa_fp16_overflow 0
		.amdhsa_tg_split 0
		.amdhsa_exception_fp_ieee_invalid_op 0
		.amdhsa_exception_fp_denorm_src 0
		.amdhsa_exception_fp_ieee_div_zero 0
		.amdhsa_exception_fp_ieee_overflow 0
		.amdhsa_exception_fp_ieee_underflow 0
		.amdhsa_exception_fp_ieee_inexact 0
		.amdhsa_exception_int_div_zero 0
	.end_amdhsa_kernel

amdhsa.kernels:
  - .agpr_count:     0
    .args:
      - .offset:         0
        .size:           320
        .value_kind:     by_value
      - .offset:         320
        .size:           4
        .value_kind:     hidden_block_count_x
      - .offset:         324
        .size:           4
        .value_kind:     hidden_block_count_y
      - .offset:         328
        .size:           4
        .value_kind:     hidden_block_count_z
      - .offset:         332
        .size:           2
        .value_kind:     hidden_group_size_x
      - .offset:         334
        .size:           2
        .value_kind:     hidden_group_size_y
      - .offset:         336
        .size:           2
        .value_kind:     hidden_group_size_z
      - .offset:         338
        .size:           2
        .value_kind:     hidden_remainder_x
      - .offset:         340
        .size:           2
        .value_kind:     hidden_remainder_y
      - .offset:         342
        .size:           2
        .value_kind:     hidden_remainder_z
      - .offset:         360
        .size:           8
        .value_kind:     hidden_global_offset_x
      - .offset:         368
        .size:           8
        .value_kind:     hidden_global_offset_y
      - .offset:         376
        .size:           8
        .value_kind:     hidden_global_offset_z
      - .offset:         384
        .size:           2
        .value_kind:     hidden_grid_dims
      - .offset:         408
        .size:           8
        .value_kind:     hidden_multigrid_sync_arg
      - .offset:         440
        .size:           4
        .value_kind:     hidden_dynamic_lds_size
    .group_segment_fixed_size: 0
    .kernarg_segment_align: 8
    .kernarg_segment_size: 576
    .language:       OpenCL C
    .language_version:
      - 2
      - 0
    .max_flat_workgroup_size: 512
    .name:           _Z4mega6Params
    .private_segment_fixed_size: 0
    .sgpr_count:     108
    .sgpr_spill_count: 190
    .symbol:         _Z4mega6Params.kd
    .uniform_work_group_size: 1
    .uses_dynamic_stack: false
    .vgpr_count:     256
    .vgpr_spill_count: 0
    .wavefront_size: 64
